# phase_ada silu(c) staging: 64 serial load-wait-write steps per lane become 4 batches of 16 loads with the next batch in flight (same per-element arithmetic)
# speedup vs baseline: 1.0051x; 1.0027x over previous
.LBB0_1728:
	s_and_saveexec_b64 s[2:3], vcc
	s_cbranch_execz .LBB0_1731
	v_mov_b64_e32 v[0:1], v[108:109]
	v_lshlrev_b32_e32 v2, 6, v106
	v_add_u32_e32 v3, 0x10000, v2
	s_mov_b64 s[0:1], 0x1000
	global_load_dword v38, v[0:1], off
	global_load_dword v39, v[0:1], off offset:2048
	v_lshl_add_u64 v[0:1], v[0:1], 0, s[0:1]
	global_load_dword v40, v[0:1], off
	global_load_dword v41, v[0:1], off offset:2048
	v_lshl_add_u64 v[0:1], v[0:1], 0, s[0:1]
	global_load_dword v42, v[0:1], off
	global_load_dword v43, v[0:1], off offset:2048
	v_lshl_add_u64 v[0:1], v[0:1], 0, s[0:1]
	global_load_dword v44, v[0:1], off
	global_load_dword v45, v[0:1], off offset:2048
	v_lshl_add_u64 v[0:1], v[0:1], 0, s[0:1]
	global_load_dword v46, v[0:1], off
	global_load_dword v47, v[0:1], off offset:2048
	v_lshl_add_u64 v[0:1], v[0:1], 0, s[0:1]
	global_load_dword v48, v[0:1], off
	global_load_dword v49, v[0:1], off offset:2048
	v_lshl_add_u64 v[0:1], v[0:1], 0, s[0:1]
	global_load_dword v50, v[0:1], off
	global_load_dword v51, v[0:1], off offset:2048
	v_lshl_add_u64 v[0:1], v[0:1], 0, s[0:1]
	global_load_dword v52, v[0:1], off
	global_load_dword v53, v[0:1], off offset:2048
	v_lshl_add_u64 v[0:1], v[0:1], 0, s[0:1]
	global_load_dword v54, v[0:1], off
	global_load_dword v55, v[0:1], off offset:2048
	v_lshl_add_u64 v[0:1], v[0:1], 0, s[0:1]
	global_load_dword v56, v[0:1], off
	global_load_dword v57, v[0:1], off offset:2048
	v_lshl_add_u64 v[0:1], v[0:1], 0, s[0:1]
	global_load_dword v58, v[0:1], off
	global_load_dword v59, v[0:1], off offset:2048
	v_lshl_add_u64 v[0:1], v[0:1], 0, s[0:1]
	global_load_dword v60, v[0:1], off
	global_load_dword v61, v[0:1], off offset:2048
	v_lshl_add_u64 v[0:1], v[0:1], 0, s[0:1]
	global_load_dword v62, v[0:1], off
	global_load_dword v63, v[0:1], off offset:2048
	v_lshl_add_u64 v[0:1], v[0:1], 0, s[0:1]
	global_load_dword v64, v[0:1], off
	global_load_dword v65, v[0:1], off offset:2048
	v_lshl_add_u64 v[0:1], v[0:1], 0, s[0:1]
	global_load_dword v66, v[0:1], off
	global_load_dword v67, v[0:1], off offset:2048
	v_lshl_add_u64 v[0:1], v[0:1], 0, s[0:1]
	global_load_dword v68, v[0:1], off
	global_load_dword v69, v[0:1], off offset:2048
	v_lshl_add_u64 v[0:1], v[0:1], 0, s[0:1]
	s_waitcnt vmcnt(31)
	v_mul_f32_e32 v4, 0xbfb8aa3b, v38
	v_exp_f32_e32 v4, v4
	s_nop 0
	v_add_f32_e32 v4, 1.0, v4
	v_rcp_f32_e32 v4, v4
	s_nop 0
	v_mul_f32_e32 v4, v38, v4
	ds_write_b32 v2, v4
	s_waitcnt vmcnt(30)
	v_mul_f32_e32 v4, 0xbfb8aa3b, v39
	v_exp_f32_e32 v4, v4
	s_nop 0
	v_add_f32_e32 v4, 1.0, v4
	v_rcp_f32_e32 v4, v4
	s_nop 0
	v_mul_f32_e32 v4, v39, v4
	ds_write_b32 v2, v4 offset:32768
	s_waitcnt vmcnt(29)
	v_mul_f32_e32 v4, 0xbfb8aa3b, v40
	v_exp_f32_e32 v4, v4
	s_nop 0
	v_add_f32_e32 v4, 1.0, v4
	v_rcp_f32_e32 v4, v4
	s_nop 0
	v_mul_f32_e32 v4, v40, v4
	ds_write_b32 v3, v4
	s_waitcnt vmcnt(28)
	v_mul_f32_e32 v4, 0xbfb8aa3b, v41
	v_exp_f32_e32 v4, v4
	s_nop 0
	v_add_f32_e32 v4, 1.0, v4
	v_rcp_f32_e32 v4, v4
	s_nop 0
	v_mul_f32_e32 v4, v41, v4
	ds_write_b32 v3, v4 offset:32768
	s_waitcnt vmcnt(27)
	v_mul_f32_e32 v4, 0xbfb8aa3b, v42
	v_exp_f32_e32 v4, v4
	s_nop 0
	v_add_f32_e32 v4, 1.0, v4
	v_rcp_f32_e32 v4, v4
	s_nop 0
	v_mul_f32_e32 v4, v42, v4
	ds_write_b32 v2, v4 offset:4
	s_waitcnt vmcnt(26)
	v_mul_f32_e32 v4, 0xbfb8aa3b, v43
	v_exp_f32_e32 v4, v4
	s_nop 0
	v_add_f32_e32 v4, 1.0, v4
	v_rcp_f32_e32 v4, v4
	s_nop 0
	v_mul_f32_e32 v4, v43, v4
	ds_write_b32 v2, v4 offset:32772
	s_waitcnt vmcnt(25)
	v_mul_f32_e32 v4, 0xbfb8aa3b, v44
	v_exp_f32_e32 v4, v4
	s_nop 0
	v_add_f32_e32 v4, 1.0, v4
	v_rcp_f32_e32 v4, v4
	s_nop 0
	v_mul_f32_e32 v4, v44, v4
	ds_write_b32 v3, v4 offset:4
	s_waitcnt vmcnt(24)
	v_mul_f32_e32 v4, 0xbfb8aa3b, v45
	v_exp_f32_e32 v4, v4
	s_nop 0
	v_add_f32_e32 v4, 1.0, v4
	v_rcp_f32_e32 v4, v4
	s_nop 0
	v_mul_f32_e32 v4, v45, v4
	ds_write_b32 v3, v4 offset:32772
	s_waitcnt vmcnt(23)
	v_mul_f32_e32 v4, 0xbfb8aa3b, v46
	v_exp_f32_e32 v4, v4
	s_nop 0
	v_add_f32_e32 v4, 1.0, v4
	v_rcp_f32_e32 v4, v4
	s_nop 0
	v_mul_f32_e32 v4, v46, v4
	ds_write_b32 v2, v4 offset:8
	s_waitcnt vmcnt(22)
	v_mul_f32_e32 v4, 0xbfb8aa3b, v47
	v_exp_f32_e32 v4, v4
	s_nop 0
	v_add_f32_e32 v4, 1.0, v4
	v_rcp_f32_e32 v4, v4
	s_nop 0
	v_mul_f32_e32 v4, v47, v4
	ds_write_b32 v2, v4 offset:32776
	s_waitcnt vmcnt(21)
	v_mul_f32_e32 v4, 0xbfb8aa3b, v48
	v_exp_f32_e32 v4, v4
	s_nop 0
	v_add_f32_e32 v4, 1.0, v4
	v_rcp_f32_e32 v4, v4
	s_nop 0
	v_mul_f32_e32 v4, v48, v4
	ds_write_b32 v3, v4 offset:8
	s_waitcnt vmcnt(20)
	v_mul_f32_e32 v4, 0xbfb8aa3b, v49
	v_exp_f32_e32 v4, v4
	s_nop 0
	v_add_f32_e32 v4, 1.0, v4
	v_rcp_f32_e32 v4, v4
	s_nop 0
	v_mul_f32_e32 v4, v49, v4
	ds_write_b32 v3, v4 offset:32776
	s_waitcnt vmcnt(19)
	v_mul_f32_e32 v4, 0xbfb8aa3b, v50
	v_exp_f32_e32 v4, v4
	s_nop 0
	v_add_f32_e32 v4, 1.0, v4
	v_rcp_f32_e32 v4, v4
	s_nop 0
	v_mul_f32_e32 v4, v50, v4
	ds_write_b32 v2, v4 offset:12
	s_waitcnt vmcnt(18)
	v_mul_f32_e32 v4, 0xbfb8aa3b, v51
	v_exp_f32_e32 v4, v4
	s_nop 0
	v_add_f32_e32 v4, 1.0, v4
	v_rcp_f32_e32 v4, v4
	s_nop 0
	v_mul_f32_e32 v4, v51, v4
	ds_write_b32 v2, v4 offset:32780
	s_waitcnt vmcnt(17)
	v_mul_f32_e32 v4, 0xbfb8aa3b, v52
	v_exp_f32_e32 v4, v4
	s_nop 0
	v_add_f32_e32 v4, 1.0, v4
	v_rcp_f32_e32 v4, v4
	s_nop 0
	v_mul_f32_e32 v4, v52, v4
	ds_write_b32 v3, v4 offset:12
	s_waitcnt vmcnt(16)
	v_mul_f32_e32 v4, 0xbfb8aa3b, v53
	v_exp_f32_e32 v4, v4
	s_nop 0
	v_add_f32_e32 v4, 1.0, v4
	v_rcp_f32_e32 v4, v4
	s_nop 0
	v_mul_f32_e32 v4, v53, v4
	ds_write_b32 v3, v4 offset:32780
	global_load_dword v38, v[0:1], off
	global_load_dword v39, v[0:1], off offset:2048
	v_lshl_add_u64 v[0:1], v[0:1], 0, s[0:1]
	global_load_dword v40, v[0:1], off
	global_load_dword v41, v[0:1], off offset:2048
	v_lshl_add_u64 v[0:1], v[0:1], 0, s[0:1]
	global_load_dword v42, v[0:1], off
	global_load_dword v43, v[0:1], off offset:2048
	v_lshl_add_u64 v[0:1], v[0:1], 0, s[0:1]
	global_load_dword v44, v[0:1], off
	global_load_dword v45, v[0:1], off offset:2048
	v_lshl_add_u64 v[0:1], v[0:1], 0, s[0:1]
	global_load_dword v46, v[0:1], off
	global_load_dword v47, v[0:1], off offset:2048
	v_lshl_add_u64 v[0:1], v[0:1], 0, s[0:1]
	global_load_dword v48, v[0:1], off
	global_load_dword v49, v[0:1], off offset:2048
	v_lshl_add_u64 v[0:1], v[0:1], 0, s[0:1]
	global_load_dword v50, v[0:1], off
	global_load_dword v51, v[0:1], off offset:2048
	v_lshl_add_u64 v[0:1], v[0:1], 0, s[0:1]
	global_load_dword v52, v[0:1], off
	global_load_dword v53, v[0:1], off offset:2048
	v_lshl_add_u64 v[0:1], v[0:1], 0, s[0:1]
	s_waitcnt vmcnt(31)
	v_mul_f32_e32 v4, 0xbfb8aa3b, v54
	v_exp_f32_e32 v4, v4
	s_nop 0
	v_add_f32_e32 v4, 1.0, v4
	v_rcp_f32_e32 v4, v4
	s_nop 0
	v_mul_f32_e32 v4, v54, v4
	ds_write_b32 v2, v4 offset:16
	s_waitcnt vmcnt(30)
	v_mul_f32_e32 v4, 0xbfb8aa3b, v55
	v_exp_f32_e32 v4, v4
	s_nop 0
	v_add_f32_e32 v4, 1.0, v4
	v_rcp_f32_e32 v4, v4
	s_nop 0
	v_mul_f32_e32 v4, v55, v4
	ds_write_b32 v2, v4 offset:32784
	s_waitcnt vmcnt(29)
	v_mul_f32_e32 v4, 0xbfb8aa3b, v56
	v_exp_f32_e32 v4, v4
	s_nop 0
	v_add_f32_e32 v4, 1.0, v4
	v_rcp_f32_e32 v4, v4
	s_nop 0
	v_mul_f32_e32 v4, v56, v4
	ds_write_b32 v3, v4 offset:16
	s_waitcnt vmcnt(28)
	v_mul_f32_e32 v4, 0xbfb8aa3b, v57
	v_exp_f32_e32 v4, v4
	s_nop 0
	v_add_f32_e32 v4, 1.0, v4
	v_rcp_f32_e32 v4, v4
	s_nop 0
	v_mul_f32_e32 v4, v57, v4
	ds_write_b32 v3, v4 offset:32784
	s_waitcnt vmcnt(27)
	v_mul_f32_e32 v4, 0xbfb8aa3b, v58
	v_exp_f32_e32 v4, v4
	s_nop 0
	v_add_f32_e32 v4, 1.0, v4
	v_rcp_f32_e32 v4, v4
	s_nop 0
	v_mul_f32_e32 v4, v58, v4
	ds_write_b32 v2, v4 offset:20
	s_waitcnt vmcnt(26)
	v_mul_f32_e32 v4, 0xbfb8aa3b, v59
	v_exp_f32_e32 v4, v4
	s_nop 0
	v_add_f32_e32 v4, 1.0, v4
	v_rcp_f32_e32 v4, v4
	s_nop 0
	v_mul_f32_e32 v4, v59, v4
	ds_write_b32 v2, v4 offset:32788
	s_waitcnt vmcnt(25)
	v_mul_f32_e32 v4, 0xbfb8aa3b, v60
	v_exp_f32_e32 v4, v4
	s_nop 0
	v_add_f32_e32 v4, 1.0, v4
	v_rcp_f32_e32 v4, v4
	s_nop 0
	v_mul_f32_e32 v4, v60, v4
	ds_write_b32 v3, v4 offset:20
	s_waitcnt vmcnt(24)
	v_mul_f32_e32 v4, 0xbfb8aa3b, v61
	v_exp_f32_e32 v4, v4
	s_nop 0
	v_add_f32_e32 v4, 1.0, v4
	v_rcp_f32_e32 v4, v4
	s_nop 0
	v_mul_f32_e32 v4, v61, v4
	ds_write_b32 v3, v4 offset:32788
	s_waitcnt vmcnt(23)
	v_mul_f32_e32 v4, 0xbfb8aa3b, v62
	v_exp_f32_e32 v4, v4
	s_nop 0
	v_add_f32_e32 v4, 1.0, v4
	v_rcp_f32_e32 v4, v4
	s_nop 0
	v_mul_f32_e32 v4, v62, v4
	ds_write_b32 v2, v4 offset:24
	s_waitcnt vmcnt(22)
	v_mul_f32_e32 v4, 0xbfb8aa3b, v63
	v_exp_f32_e32 v4, v4
	s_nop 0
	v_add_f32_e32 v4, 1.0, v4
	v_rcp_f32_e32 v4, v4
	s_nop 0
	v_mul_f32_e32 v4, v63, v4
	ds_write_b32 v2, v4 offset:32792
	s_waitcnt vmcnt(21)
	v_mul_f32_e32 v4, 0xbfb8aa3b, v64
	v_exp_f32_e32 v4, v4
	s_nop 0
	v_add_f32_e32 v4, 1.0, v4
	v_rcp_f32_e32 v4, v4
	s_nop 0
	v_mul_f32_e32 v4, v64, v4
	ds_write_b32 v3, v4 offset:24
	s_waitcnt vmcnt(20)
	v_mul_f32_e32 v4, 0xbfb8aa3b, v65
	v_exp_f32_e32 v4, v4
	s_nop 0
	v_add_f32_e32 v4, 1.0, v4
	v_rcp_f32_e32 v4, v4
	s_nop 0
	v_mul_f32_e32 v4, v65, v4
	ds_write_b32 v3, v4 offset:32792
	s_waitcnt vmcnt(19)
	v_mul_f32_e32 v4, 0xbfb8aa3b, v66
	v_exp_f32_e32 v4, v4
	s_nop 0
	v_add_f32_e32 v4, 1.0, v4
	v_rcp_f32_e32 v4, v4
	s_nop 0
	v_mul_f32_e32 v4, v66, v4
	ds_write_b32 v2, v4 offset:28
	s_waitcnt vmcnt(18)
	v_mul_f32_e32 v4, 0xbfb8aa3b, v67
	v_exp_f32_e32 v4, v4
	s_nop 0
	v_add_f32_e32 v4, 1.0, v4
	v_rcp_f32_e32 v4, v4
	s_nop 0
	v_mul_f32_e32 v4, v67, v4
	ds_write_b32 v2, v4 offset:32796
	s_waitcnt vmcnt(17)
	v_mul_f32_e32 v4, 0xbfb8aa3b, v68
	v_exp_f32_e32 v4, v4
	s_nop 0
	v_add_f32_e32 v4, 1.0, v4
	v_rcp_f32_e32 v4, v4
	s_nop 0
	v_mul_f32_e32 v4, v68, v4
	ds_write_b32 v3, v4 offset:28
	s_waitcnt vmcnt(16)
	v_mul_f32_e32 v4, 0xbfb8aa3b, v69
	v_exp_f32_e32 v4, v4
	s_nop 0
	v_add_f32_e32 v4, 1.0, v4
	v_rcp_f32_e32 v4, v4
	s_nop 0
	v_mul_f32_e32 v4, v69, v4
	ds_write_b32 v3, v4 offset:32796
	global_load_dword v54, v[0:1], off
	global_load_dword v55, v[0:1], off offset:2048
	v_lshl_add_u64 v[0:1], v[0:1], 0, s[0:1]
	global_load_dword v56, v[0:1], off
	global_load_dword v57, v[0:1], off offset:2048
	v_lshl_add_u64 v[0:1], v[0:1], 0, s[0:1]
	global_load_dword v58, v[0:1], off
	global_load_dword v59, v[0:1], off offset:2048
	v_lshl_add_u64 v[0:1], v[0:1], 0, s[0:1]
	global_load_dword v60, v[0:1], off
	global_load_dword v61, v[0:1], off offset:2048
	v_lshl_add_u64 v[0:1], v[0:1], 0, s[0:1]
	global_load_dword v62, v[0:1], off
	global_load_dword v63, v[0:1], off offset:2048
	v_lshl_add_u64 v[0:1], v[0:1], 0, s[0:1]
	global_load_dword v64, v[0:1], off
	global_load_dword v65, v[0:1], off offset:2048
	v_lshl_add_u64 v[0:1], v[0:1], 0, s[0:1]
	global_load_dword v66, v[0:1], off
	global_load_dword v67, v[0:1], off offset:2048
	v_lshl_add_u64 v[0:1], v[0:1], 0, s[0:1]
	global_load_dword v68, v[0:1], off
	global_load_dword v69, v[0:1], off offset:2048
	v_lshl_add_u64 v[0:1], v[0:1], 0, s[0:1]
	s_waitcnt vmcnt(31)
	v_mul_f32_e32 v4, 0xbfb8aa3b, v38
	v_exp_f32_e32 v4, v4
	s_nop 0
	v_add_f32_e32 v4, 1.0, v4
	v_rcp_f32_e32 v4, v4
	s_nop 0
	v_mul_f32_e32 v4, v38, v4
	ds_write_b32 v2, v4 offset:32
	s_waitcnt vmcnt(30)
	v_mul_f32_e32 v4, 0xbfb8aa3b, v39
	v_exp_f32_e32 v4, v4
	s_nop 0
	v_add_f32_e32 v4, 1.0, v4
	v_rcp_f32_e32 v4, v4
	s_nop 0
	v_mul_f32_e32 v4, v39, v4
	ds_write_b32 v2, v4 offset:32800
	s_waitcnt vmcnt(29)
	v_mul_f32_e32 v4, 0xbfb8aa3b, v40
	v_exp_f32_e32 v4, v4
	s_nop 0
	v_add_f32_e32 v4, 1.0, v4
	v_rcp_f32_e32 v4, v4
	s_nop 0
	v_mul_f32_e32 v4, v40, v4
	ds_write_b32 v3, v4 offset:32
	s_waitcnt vmcnt(28)
	v_mul_f32_e32 v4, 0xbfb8aa3b, v41
	v_exp_f32_e32 v4, v4
	s_nop 0
	v_add_f32_e32 v4, 1.0, v4
	v_rcp_f32_e32 v4, v4
	s_nop 0
	v_mul_f32_e32 v4, v41, v4
	ds_write_b32 v3, v4 offset:32800
	s_waitcnt vmcnt(27)
	v_mul_f32_e32 v4, 0xbfb8aa3b, v42
	v_exp_f32_e32 v4, v4
	s_nop 0
	v_add_f32_e32 v4, 1.0, v4
	v_rcp_f32_e32 v4, v4
	s_nop 0
	v_mul_f32_e32 v4, v42, v4
	ds_write_b32 v2, v4 offset:36
	s_waitcnt vmcnt(26)
	v_mul_f32_e32 v4, 0xbfb8aa3b, v43
	v_exp_f32_e32 v4, v4
	s_nop 0
	v_add_f32_e32 v4, 1.0, v4
	v_rcp_f32_e32 v4, v4
	s_nop 0
	v_mul_f32_e32 v4, v43, v4
	ds_write_b32 v2, v4 offset:32804
	s_waitcnt vmcnt(25)
	v_mul_f32_e32 v4, 0xbfb8aa3b, v44
	v_exp_f32_e32 v4, v4
	s_nop 0
	v_add_f32_e32 v4, 1.0, v4
	v_rcp_f32_e32 v4, v4
	s_nop 0
	v_mul_f32_e32 v4, v44, v4
	ds_write_b32 v3, v4 offset:36
	s_waitcnt vmcnt(24)
	v_mul_f32_e32 v4, 0xbfb8aa3b, v45
	v_exp_f32_e32 v4, v4
	s_nop 0
	v_add_f32_e32 v4, 1.0, v4
	v_rcp_f32_e32 v4, v4
	s_nop 0
	v_mul_f32_e32 v4, v45, v4
	ds_write_b32 v3, v4 offset:32804
	s_waitcnt vmcnt(23)
	v_mul_f32_e32 v4, 0xbfb8aa3b, v46
	v_exp_f32_e32 v4, v4
	s_nop 0
	v_add_f32_e32 v4, 1.0, v4
	v_rcp_f32_e32 v4, v4
	s_nop 0
	v_mul_f32_e32 v4, v46, v4
	ds_write_b32 v2, v4 offset:40
	s_waitcnt vmcnt(22)
	v_mul_f32_e32 v4, 0xbfb8aa3b, v47
	v_exp_f32_e32 v4, v4
	s_nop 0
	v_add_f32_e32 v4, 1.0, v4
	v_rcp_f32_e32 v4, v4
	s_nop 0
	v_mul_f32_e32 v4, v47, v4
	ds_write_b32 v2, v4 offset:32808
	s_waitcnt vmcnt(21)
	v_mul_f32_e32 v4, 0xbfb8aa3b, v48
	v_exp_f32_e32 v4, v4
	s_nop 0
	v_add_f32_e32 v4, 1.0, v4
	v_rcp_f32_e32 v4, v4
	s_nop 0
	v_mul_f32_e32 v4, v48, v4
	ds_write_b32 v3, v4 offset:40
	s_waitcnt vmcnt(20)
	v_mul_f32_e32 v4, 0xbfb8aa3b, v49
	v_exp_f32_e32 v4, v4
	s_nop 0
	v_add_f32_e32 v4, 1.0, v4
	v_rcp_f32_e32 v4, v4
	s_nop 0
	v_mul_f32_e32 v4, v49, v4
	ds_write_b32 v3, v4 offset:32808
	s_waitcnt vmcnt(19)
	v_mul_f32_e32 v4, 0xbfb8aa3b, v50
	v_exp_f32_e32 v4, v4
	s_nop 0
	v_add_f32_e32 v4, 1.0, v4
	v_rcp_f32_e32 v4, v4
	s_nop 0
	v_mul_f32_e32 v4, v50, v4
	ds_write_b32 v2, v4 offset:44
	s_waitcnt vmcnt(18)
	v_mul_f32_e32 v4, 0xbfb8aa3b, v51
	v_exp_f32_e32 v4, v4
	s_nop 0
	v_add_f32_e32 v4, 1.0, v4
	v_rcp_f32_e32 v4, v4
	s_nop 0
	v_mul_f32_e32 v4, v51, v4
	ds_write_b32 v2, v4 offset:32812
	s_waitcnt vmcnt(17)
	v_mul_f32_e32 v4, 0xbfb8aa3b, v52
	v_exp_f32_e32 v4, v4
	s_nop 0
	v_add_f32_e32 v4, 1.0, v4
	v_rcp_f32_e32 v4, v4
	s_nop 0
	v_mul_f32_e32 v4, v52, v4
	ds_write_b32 v3, v4 offset:44
	s_waitcnt vmcnt(16)
	v_mul_f32_e32 v4, 0xbfb8aa3b, v53
	v_exp_f32_e32 v4, v4
	s_nop 0
	v_add_f32_e32 v4, 1.0, v4
	v_rcp_f32_e32 v4, v4
	s_nop 0
	v_mul_f32_e32 v4, v53, v4
	ds_write_b32 v3, v4 offset:32812
	s_waitcnt vmcnt(15)
	v_mul_f32_e32 v4, 0xbfb8aa3b, v54
	v_exp_f32_e32 v4, v4
	s_nop 0
	v_add_f32_e32 v4, 1.0, v4
	v_rcp_f32_e32 v4, v4
	s_nop 0
	v_mul_f32_e32 v4, v54, v4
	ds_write_b32 v2, v4 offset:48
	s_waitcnt vmcnt(14)
	v_mul_f32_e32 v4, 0xbfb8aa3b, v55
	v_exp_f32_e32 v4, v4
	s_nop 0
	v_add_f32_e32 v4, 1.0, v4
	v_rcp_f32_e32 v4, v4
	s_nop 0
	v_mul_f32_e32 v4, v55, v4
	ds_write_b32 v2, v4 offset:32816
	s_waitcnt vmcnt(13)
	v_mul_f32_e32 v4, 0xbfb8aa3b, v56
	v_exp_f32_e32 v4, v4
	s_nop 0
	v_add_f32_e32 v4, 1.0, v4
	v_rcp_f32_e32 v4, v4
	s_nop 0
	v_mul_f32_e32 v4, v56, v4
	ds_write_b32 v3, v4 offset:48
	s_waitcnt vmcnt(12)
	v_mul_f32_e32 v4, 0xbfb8aa3b, v57
	v_exp_f32_e32 v4, v4
	s_nop 0
	v_add_f32_e32 v4, 1.0, v4
	v_rcp_f32_e32 v4, v4
	s_nop 0
	v_mul_f32_e32 v4, v57, v4
	ds_write_b32 v3, v4 offset:32816
	s_waitcnt vmcnt(11)
	v_mul_f32_e32 v4, 0xbfb8aa3b, v58
	v_exp_f32_e32 v4, v4
	s_nop 0
	v_add_f32_e32 v4, 1.0, v4
	v_rcp_f32_e32 v4, v4
	s_nop 0
	v_mul_f32_e32 v4, v58, v4
	ds_write_b32 v2, v4 offset:52
	s_waitcnt vmcnt(10)
	v_mul_f32_e32 v4, 0xbfb8aa3b, v59
	v_exp_f32_e32 v4, v4
	s_nop 0
	v_add_f32_e32 v4, 1.0, v4
	v_rcp_f32_e32 v4, v4
	s_nop 0
	v_mul_f32_e32 v4, v59, v4
	ds_write_b32 v2, v4 offset:32820
	s_waitcnt vmcnt(9)
	v_mul_f32_e32 v4, 0xbfb8aa3b, v60
	v_exp_f32_e32 v4, v4
	s_nop 0
	v_add_f32_e32 v4, 1.0, v4
	v_rcp_f32_e32 v4, v4
	s_nop 0
	v_mul_f32_e32 v4, v60, v4
	ds_write_b32 v3, v4 offset:52
	s_waitcnt vmcnt(8)
	v_mul_f32_e32 v4, 0xbfb8aa3b, v61
	v_exp_f32_e32 v4, v4
	s_nop 0
	v_add_f32_e32 v4, 1.0, v4
	v_rcp_f32_e32 v4, v4
	s_nop 0
	v_mul_f32_e32 v4, v61, v4
	ds_write_b32 v3, v4 offset:32820
	s_waitcnt vmcnt(7)
	v_mul_f32_e32 v4, 0xbfb8aa3b, v62
	v_exp_f32_e32 v4, v4
	s_nop 0
	v_add_f32_e32 v4, 1.0, v4
	v_rcp_f32_e32 v4, v4
	s_nop 0
	v_mul_f32_e32 v4, v62, v4
	ds_write_b32 v2, v4 offset:56
	s_waitcnt vmcnt(6)
	v_mul_f32_e32 v4, 0xbfb8aa3b, v63
	v_exp_f32_e32 v4, v4
	s_nop 0
	v_add_f32_e32 v4, 1.0, v4
	v_rcp_f32_e32 v4, v4
	s_nop 0
	v_mul_f32_e32 v4, v63, v4
	ds_write_b32 v2, v4 offset:32824
	s_waitcnt vmcnt(5)
	v_mul_f32_e32 v4, 0xbfb8aa3b, v64
	v_exp_f32_e32 v4, v4
	s_nop 0
	v_add_f32_e32 v4, 1.0, v4
	v_rcp_f32_e32 v4, v4
	s_nop 0
	v_mul_f32_e32 v4, v64, v4
	ds_write_b32 v3, v4 offset:56
	s_waitcnt vmcnt(4)
	v_mul_f32_e32 v4, 0xbfb8aa3b, v65
	v_exp_f32_e32 v4, v4
	s_nop 0
	v_add_f32_e32 v4, 1.0, v4
	v_rcp_f32_e32 v4, v4
	s_nop 0
	v_mul_f32_e32 v4, v65, v4
	ds_write_b32 v3, v4 offset:32824
	s_waitcnt vmcnt(3)
	v_mul_f32_e32 v4, 0xbfb8aa3b, v66
	v_exp_f32_e32 v4, v4
	s_nop 0
	v_add_f32_e32 v4, 1.0, v4
	v_rcp_f32_e32 v4, v4
	s_nop 0
	v_mul_f32_e32 v4, v66, v4
	ds_write_b32 v2, v4 offset:60
	s_waitcnt vmcnt(2)
	v_mul_f32_e32 v4, 0xbfb8aa3b, v67
	v_exp_f32_e32 v4, v4
	s_nop 0
	v_add_f32_e32 v4, 1.0, v4
	v_rcp_f32_e32 v4, v4
	s_nop 0
	v_mul_f32_e32 v4, v67, v4
	ds_write_b32 v2, v4 offset:32828
	s_waitcnt vmcnt(1)
	v_mul_f32_e32 v4, 0xbfb8aa3b, v68
	v_exp_f32_e32 v4, v4
	s_nop 0
	v_add_f32_e32 v4, 1.0, v4
	v_rcp_f32_e32 v4, v4
	s_nop 0
	v_mul_f32_e32 v4, v68, v4
	ds_write_b32 v3, v4 offset:60
	s_waitcnt vmcnt(0)
	v_mul_f32_e32 v4, 0xbfb8aa3b, v69
	v_exp_f32_e32 v4, v4
	s_nop 0
	v_add_f32_e32 v4, 1.0, v4
	v_rcp_f32_e32 v4, v4
	s_nop 0
	v_mul_f32_e32 v4, v69, v4
	ds_write_b32 v3, v4 offset:32828
